# P1 reorder: waves 2-7 run the weight conversion before their sample SSM tasks (flag s101, save/restore s12-15,s48-49)
# speedup vs baseline: 1.0060x; 1.0018x over previous
.LBB0_77:
	s_mov_b32 s101, 0
	s_cmp_gt_i32 s96, 1
	s_cselect_b64 s[0:1], -1, 0
	s_cmp_lt_i32 s97, 2
	s_cselect_b64 s[2:3], -1, 0
	s_or_b64 s[0:1], s[0:1], s[2:3]
	s_and_b64 vcc, exec, s[0:1]
	s_cbranch_vccnz .LBB0_170
	s_cmpk_gt_u32 s63, 0x7f
	s_mov_b64 s[0:1], -1
	s_cbranch_scc0 .LBB0_83
	s_mov_b32 s101, 1
	v_writelane_b32 v254, s12, 0
	v_writelane_b32 v254, s13, 1
	v_writelane_b32 v254, s14, 2
	v_writelane_b32 v254, s15, 3
	v_writelane_b32 v254, s48, 4
	v_writelane_b32 v254, s49, 5
	s_branch .LBB0_89
.Lp1_sample:
	s_mov_b32 s101, 2
	v_readlane_b32 s12, v254, 0
	v_readlane_b32 s13, v254, 1
	v_readlane_b32 s14, v254, 2
	v_readlane_b32 s15, v254, 3
	v_readlane_b32 s48, v254, 4
	v_readlane_b32 s49, v254, 5
	s_waitcnt vmcnt(0) lgkmcnt(0)
	s_mul_i32 s0, s94, 6
	s_add_i32 s0, s93, s0
	s_add_i32 s30, s0, -2
	s_cmpk_gt_i32 s30, 0x1fff
	s_cbranch_scc1 .LBB0_82
	s_add_u32 s0, s84, 0x48c00000
	s_addc_u32 s1, s85, 0
	s_add_u32 s2, s84, 0x48c20000
	s_addc_u32 s3, s85, 0
	s_add_u32 s4, s84, 0x48d20000
	s_addc_u32 s5, s85, 0
	v_lshrrev_b32_e32 v1, 2, v0
	s_add_u32 s6, s84, 0x48c10000
	v_and_b32_e32 v2, 12, v1
	v_and_b32_e32 v1, 3, v0
	v_lshrrev_b32_e32 v4, 1, v154
	s_mul_i32 s22, s93, 0x2200
	s_addc_u32 s7, s85, 0
	v_and_or_b32 v5, v4, 4, v1
	s_add_i32 s22, s22, 0
	v_lshrrev_b32_e32 v3, 5, v154
	v_or_b32_e32 v87, 0x2000, v5
	v_or_b32_e32 v89, 0x2008, v5
	s_movk_i32 s24, 0x440
	v_mov_b32_e32 v5, s22
	v_mad_u32_u24 v9, v3, s24, v5
	s_add_u32 s24, s90, 0x9170000
	s_addc_u32 s25, s91, 0
	v_and_b32_e32 v68, 31, v0
	v_mov_b32_e32 v71, 0
	v_lshlrev_b32_e32 v70, 2, v2
	v_and_b32_e32 v1, 2, v4
	v_lshrrev_b32_e32 v4, 4, v0
	s_add_u32 s26, s90, 0x9970000
	s_waitcnt lgkmcnt(0)
	v_lshl_add_u64 v[72:73], s[48:49], 0, v[70:71]
	v_lshl_add_u64 v[74:75], s[18:19], 0, v[70:71]
	v_lshlrev_b32_e32 v8, 2, v68
	v_and_or_b32 v69, v4, 1, v1
	v_lshlrev_b32_e32 v91, 1, v3
	s_addc_u32 s27, s91, 0
	v_lshlrev_b32_e32 v4, 3, v3
	v_and_b32_e32 v3, 15, v0
	s_movk_i32 s22, 0x110
	v_lshlrev_b32_e32 v70, 1, v2
	s_add_u32 s28, s84, 0x49100000
	v_mad_u32_u24 v3, v3, s22, v5
	v_and_b32_e32 v5, 48, v0
	v_lshl_add_u64 v[6:7], s[84:85], 0, v[70:71]
	s_mov_b64 s[34:35], 0x33800000
	v_add_u32_e32 v101, v9, v8
	s_movk_i32 s31, 0x2000
	s_mov_b32 s23, 0
	s_addc_u32 s29, s85, 0
	v_lshl_add_u64 v[76:77], v[6:7], 0, s[34:35]
	s_mul_i32 s33, s92, 6
	v_lshlrev_b32_e32 v93, 4, v154
	v_mov_b32_e32 v97, s11
	v_mov_b32_e32 v98, s9
	v_mov_b32_e32 v99, s10
	v_mov_b32_e32 v100, s8
	v_lshlrev_b32_e32 v70, 2, v4
	v_lshlrev_b32_e32 v78, 2, v2
	v_mov_b32_e32 v79, v71
	v_add_u32_e32 v102, v3, v5
	v_add_u32_e32 v103, 0x800, v101
	v_add_u32_e32 v104, 0xa00, v101
	v_add_u32_e32 v105, 0x1000, v101
	v_add_u32_e32 v106, 0x1400, v101
	v_add_u32_e32 v107, 0x1800, v101
	v_add_u32_e32 v108, 0x1a00, v101
	v_add_u32_e32 v109, 0x1c00, v101

.LBB0_89:
	s_cmp_eq_u32 s101, 2
	s_cbranch_scc1 .LBB0_120
	v_lshlrev_b32_e32 v1, 2, v0
	s_cmpk_eq_i32 s92, 0x100
	s_movk_i32 s0, 0x7600
	v_and_b32_e32 v68, 28, v1
	s_cselect_b32 s4, s0, 0xa100
	s_ashr_i32 s30, s94, 31
	s_ashr_i32 s31, s92, 31
	v_and_b32_e32 v66, 56, v0
	v_mov_b32_e32 v71, 0
	v_lshlrev_b32_e32 v70, 2, v68
	s_cmp_lg_u64 s[20:21], 0
	s_waitcnt lgkmcnt(0)
	v_lshl_add_u64 v[72:73], s[50:51], 0, v[70:71]
	v_lshlrev_b32_e32 v70, 1, v66
	s_mov_b32 s5, 0
	s_cselect_b64 s[2:3], -1, 0
	s_add_u32 s33, s84, 0x25400000
	v_lshl_add_u64 v[2:3], s[84:85], 0, v[70:71]
	s_mov_b64 s[6:7], 0x1000000
	v_cmp_eq_u32_e64 s[0:1], 0, v154
	s_addc_u32 s34, s85, 0
	v_lshl_add_u64 v[74:75], v[2:3], 0, s[6:7]
	s_add_i32 s35, 0, 0x20190
	v_mov_b64_e32 v[76:77], s[4:5]
	s_movk_i32 s36, 0x2b00
	s_movk_i32 s37, 0x5000
	s_mov_b32 s38, 0xa000
	s_mov_b32 s39, 0x10000
	s_mov_b32 s40, 0xac000
	s_mov_b32 s41, 0xb1000
	s_mov_b32 s42, 0xb6000
	s_mov_b64 s[4:5], 0xbc200
	s_mov_b32 s43, 0x15800
	s_movk_i32 s44, 0x1000
	s_mov_b64 s[6:7], 0x80
	s_mov_b32 s45, 0x11000
	s_mov_b64 s[12:13], 0x11800
	v_lshlrev_b32_e32 v70, 2, v68
	v_lshlrev_b32_e32 v78, 1, v66
	s_branch .LBB0_92

.LBB0_120:
	s_cmp_eq_u32 s101, 1
	s_cbranch_scc1 .Lp1_sample
	s_cmp_lt_i32 s97, 3
	s_cbranch_scc1 .LBB0_170
	s_waitcnt vmcnt(0)
	v_cmp_eq_u32_e32 vcc, 0, v0
	s_barrier
	s_and_saveexec_b64 s[0:1], vcc
	s_cbranch_execz .LBB0_169
	v_readlane_b32 s2, v240, 12
	s_waitcnt vmcnt(0) expcnt(0) lgkmcnt(0)
	s_nop 0
	v_mov_b32_e32 v1, s2
	ds_read_b32 v3, v1
	ds_read_b32 v1, v1 offset:4
	s_waitcnt lgkmcnt(1)
	v_cmp_ne_u32_e32 vcc, 0, v3
	s_cbranch_vccnz .LBB0_137
	v_readlane_b32 s2, v240, 0
	v_readlane_b32 s3, v240, 1
	s_load_dwordx2 s[6:7], s[2:3], 0x4
	s_add_u32 s2, s84, 0x4200
	s_addc_u32 s3, s85, 0
	s_add_u32 s4, s84, 0x4400
	s_addc_u32 s5, s85, 0
	s_waitcnt lgkmcnt(0)
	s_mul_i32 s33, s6, s92
	s_add_u32 s6, s84, 0x4500
	s_mul_i32 s33, s33, s7
	s_addc_u32 s7, s85, 0
	s_add_u32 s12, s84, 0x4600
	s_addc_u32 s13, s85, 0
	s_add_u32 s14, s84, 0x4700
	s_addc_u32 s15, s85, 0
	s_add_u32 s22, s84, 0x4800
	s_addc_u32 s23, s85, 0
	s_add_u32 s24, s84, 0x4900
	s_addc_u32 s25, s85, 0
	s_add_u32 s26, s84, 0x4a00
	s_addc_u32 s27, s85, 0
	s_add_u32 s28, s84, 0x4b00
	s_addc_u32 s29, s85, 0
	s_add_u32 s30, s84, 0x4c00
	s_addc_u32 s31, s85, 0
	s_add_u32 s34, s84, 0x4d00
	s_addc_u32 s35, s85, 0
	s_add_u32 s36, s84, 0x4e00
	s_addc_u32 s37, s85, 0
	s_add_u32 s38, s84, 0x4f00
	s_addc_u32 s39, s85, 0
	s_add_u32 s40, s84, 0x5000
	s_addc_u32 s41, s85, 0
	s_add_u32 s42, s84, 0x5100
	s_addc_u32 s43, s85, 0
	s_add_u32 s44, s84, 0x5200
	s_addc_u32 s45, s85, 0
	s_add_u32 s46, s84, 0x5300
	s_addc_u32 s47, s85, 0
	s_mov_b32 s56, 1
	v_mov_b32_e32 v17, 0
	s_branch .LBB0_125
